# prep maps: next column block's weight fragments fetched before the current block's stores; out mLSTM items: operand loads issued before the gate-scalar wait
# baseline (speedup 1.0000x reference)
; DI int crow(int i, int hh) { return (i & 3) + 8 * (i >> 2) + 4 * hh; }
; #define MFMA32(a, b, c) __builtin_amdgcn_mfma_f32_32x32x16_bf16((a), (b), (c), 0, 0, 0)
; template <int BR> DI void out_item(PARAMS P, int l, int cid, int h, LAS unsigned char* lds, int wave, int lane) {
;     ...
;     if (BR == 1) {
;         mp = ((const float*)(P.ws + WS_MP))[cid * 4 + h];
;         if (tid < 64) { const f32x4 ts = ((const f32x4*)(P.ws + WS_TS))[(size_t)(row0 + tid) * 4 + h]; Al[tid] = ts[0]; Gl[tid] = ts[1]; Bl[tid] = ts[2]; }
;         __syncthreads();
;     }
;     f32x16 o;
; #pragma unroll
;     for (int i = 0; i < 16; ++i) o[i] = 0.f;
; #pragma unroll
;     for (int ks = 0; ks < NKS; ++ks) {
;         const bf16x8 a = *(const bf16x8*)(Q + (size_t)(32 * tt + r) * QW + 16 * ks + 8 * hh);
;         typedef short s16x4_o __attribute__((ext_vector_type(4)));
;         const bf16_t* stp = ST + (size_t)((((ks >> 1) * 4 + 2 * (ks & 1) + hh) * 2) * 128 + 32 * vt + r) * 4;
;         const s16x4_o b0_ = *(const s16x4_o*)stp, b1_ = *(const s16x4_o*)(stp + 512);
;         const bf16x8 b = __builtin_shufflevector(b0_, b1_, 0, 1, 2, 3, 4, 5, 6, 7);
;         o = MFMA32(a, b, o);
;     }
;     if (BR == 1) {
; #pragma unroll
;         for (int i = 0; i < 16; ++i) o[i] *= __expf(mp - fmaxf(mp, Gl[32 * tt + crow(i, hh)]));
;     }
;     if (wave < 4) {
;         const int ts = wave >> 1, ss = wave & 1; f32x16 p;
; #pragma unroll
;         for (int i = 0; i < 16; ++i) p[i] = 0.f;
;         if (ss <= ts) {
; #pragma unroll
;             for (int ks = 0; ks < NKS; ++ks) {
;                 const bf16x8 a = *(const bf16x8*)(Q + (size_t)(32 * ts + r) * QW + 16 * ks + 8 * hh), b = *(const bf16x8*)(K + (size_t)(32 * ss + r) * QW + 16 * ks + 8 * hh);
;                 p = MFMA32(a, b, p);
;             }
.LBB0_466:
	s_ashr_i32 s6, s1, 2
	s_mul_hi_i32 s68, s6, 0x55555556
	s_lshr_b32 s7, s68, 31
	s_add_i32 s68, s68, s7
	s_mul_i32 s7, s68, 3
	s_lshl_b32 s56, s68, 6
	s_and_b32 s3, s1, 3
	s_sub_i32 s33, s6, s7
	s_ashr_i32 s57, s56, 31
	s_mov_b64 s[8:9], -1
	s_mov_b64 s[16:17], 0
	s_cmp_lt_i32 s33, 1
	s_mov_b64 s[6:7], 0
	s_cbranch_scc1 .LBB0_508
	s_cmp_eq_u32 s33, 1
	s_mov_b64 s[6:7], -1
	s_cbranch_scc0 .LBB0_507
	s_lshl_b32 s6, s68, 2
	s_or_b32 s8, s6, s3
	s_ashr_i32 s9, s8, 31
	s_lshl_b64 s[6:7], s[8:9], 2
	v_readlane_b32 s12, v254, 36
	s_add_u32 s6, s12, s6
	v_readlane_b32 s12, v254, 37
	v_mov_b32_e32 v80, v228
	s_addc_u32 s7, s12, s7
	global_load_dword v79, v33, s[6:7]
	s_lshl_b64 s[52:53], s[56:57], 9
	s_lshl_b64 s[6:7], s[56:57], 10
	v_readlane_b32 s12, v254, 26
	s_add_u32 s6, s12, s6
	v_readlane_b32 s12, v254, 33
	s_addc_u32 s7, s12, s7
	s_lshl_b32 s48, s3, 7
	s_lshl_b32 s12, s3, 8
	s_add_u32 s6, s6, s12
	s_addc_u32 s7, s7, 0
	v_lshl_add_u64 v[0:1], s[6:7], 0, v[50:51]
	v_lshlrev_b32_e32 v32, 1, v52
	v_lshl_add_u64 v[26:27], v[0:1], 0, v[32:33]
	v_cmp_gt_i32_e32 vcc, 64, v80
	s_and_b64 exec, exec, vcc
	s_cbranch_execz .Lout_ts1
	v_add_u32_e32 v8, s56, v80
	v_ashrrev_i32_e32 v9, 31, v8
	v_readlane_b32 s20, v254, 42
	v_lshlrev_b64 v[8:9], 6, v[8:9]
	v_readlane_b32 s21, v254, 43
	s_lshl_b32 s12, s3, 4
	s_nop 0
	v_lshl_add_u64 v[8:9], s[20:21], 0, v[8:9]
	v_lshl_add_u64 v[8:9], v[8:9], 0, s[12:13]
	global_load_dwordx4 v[8:11], v[8:9], off
.Lout_ts1:
	s_mov_b64 exec, -1
	global_load_dwordx4 v[0:3], v[26:27], off
	s_lshl_b64 s[20:21], s[8:9], 15
	v_lshl_add_u64 v[16:17], v[56:57], 0, s[20:21]
	global_load_dwordx2 v[4:5], v[16:17], off
	global_load_dwordx2 v[6:7], v[16:17], off offset:1024
	global_load_dwordx4 v[18:21], v[26:27], off offset:32
	v_add_co_u32_e32 v28, vcc, 0x2000, v16
	s_nop 1
	v_addc_co_u32_e32 v29, vcc, 0, v17, vcc
	v_add_co_u32_e32 v164, vcc, 0x4000, v16
	s_nop 1
	v_addc_co_u32_e32 v165, vcc, 0, v17, vcc
	v_add_co_u32_e32 v166, vcc, 0x6000, v16
	s_nop 1
	v_addc_co_u32_e32 v167, vcc, 0, v17, vcc
	v_add_co_u32_e32 v168, vcc, 0x7000, v16
	s_nop 1
	v_addc_co_u32_e32 v169, vcc, 0, v17, vcc
	global_load_dwordx2 v[22:23], v[28:29], off offset:-4096
	global_load_dwordx2 v[24:25], v[28:29], off offset:-3072
	global_load_dwordx4 v[112:115], v[26:27], off offset:64
	global_load_dwordx2 v[116:117], v[28:29], off
	global_load_dwordx2 v[118:119], v[28:29], off offset:1024
	global_load_dwordx4 v[120:123], v[26:27], off offset:96
	global_load_dwordx2 v[124:125], v[164:165], off offset:-4096
	global_load_dwordx2 v[126:127], v[164:165], off offset:-3072
	global_load_dwordx4 v[128:131], v[26:27], off offset:128
	global_load_dwordx2 v[132:133], v[164:165], off
	global_load_dwordx2 v[134:135], v[164:165], off offset:1024
	global_load_dwordx4 v[136:139], v[26:27], off offset:160
	global_load_dwordx2 v[140:141], v[166:167], off offset:-4096
	global_load_dwordx2 v[142:143], v[166:167], off offset:-3072
	global_load_dwordx4 v[148:151], v[26:27], off offset:192
	global_load_dwordx2 v[152:153], v[168:169], off offset:-4096
	global_load_dwordx2 v[154:155], v[168:169], off offset:-3072
	global_load_dwordx4 v[156:159], v[26:27], off offset:224
	global_load_dwordx2 v[160:161], v[168:169], off
	global_load_dwordx2 v[162:163], v[168:169], off offset:1024
	v_cmp_gt_i32_e32 vcc, 64, v80
	s_and_b64 exec, exec, vcc
	s_cbranch_execz .LBB0_470
	s_waitcnt vmcnt(24)
	v_lshl_add_u32 v12, v80, 2, 0
	ds_write2st64_b32 v12, v8, v9 offset0:168 offset1:169
	ds_write_b32 v12, v10 offset:43520
.LBB0_470:
	s_mov_b64 exec, -1
	s_waitcnt lgkmcnt(0)
	s_barrier
	v_readlane_b32 s12, v254, 38
	s_nop 3
	v_add_u32_e32 v16, s12, v53
	ds_read_b128 v[46:49], v16 offset:43264
	ds_read_b128 v[42:45], v16 offset:43296
	ds_read_b128 v[38:41], v16 offset:43328
	ds_read_b128 v[34:37], v16 offset:43360
	s_andn2_b64 vcc, exec, s[40:41]
	s_waitcnt vmcnt(21)
	v_mfma_f32_32x32x16_bf16 v[0:15], v[0:3], v[4:7], 0
	s_waitcnt vmcnt(18)
	v_mfma_f32_32x32x16_bf16 v[0:15], v[18:21], v[22:25], v[0:15]
	s_waitcnt vmcnt(15)
	v_mfma_f32_32x32x16_bf16 v[0:15], v[112:115], v[116:119], v[0:15]
	s_waitcnt vmcnt(12)
	v_mfma_f32_32x32x16_bf16 v[0:15], v[120:123], v[124:127], v[0:15]
	s_waitcnt vmcnt(9)
	v_mfma_f32_32x32x16_bf16 v[0:15], v[128:131], v[132:135], v[0:15]
	s_waitcnt vmcnt(6)
	v_mfma_f32_32x32x16_bf16 v[0:15], v[136:139], v[140:143], v[0:15]
	s_waitcnt vmcnt(3)
	v_mfma_f32_32x32x16_bf16 v[0:15], v[148:151], v[152:155], v[0:15]
	s_waitcnt vmcnt(0)
	v_mfma_f32_32x32x16_bf16 v[0:15], v[156:159], v[160:163], v[0:15]
	s_cbranch_vccnz .LBB0_506
	v_mov_b32_e32 v81, 0
	s_andn2_b64 vcc, exec, s[44:45]
	v_mov_b32_e32 v16, 0
	v_mov_b32_e32 v17, 0
	v_mov_b32_e32 v18, 0
	v_mov_b32_e32 v19, 0
	v_mov_b32_e32 v20, 0
	v_mov_b32_e32 v21, 0
	v_mov_b32_e32 v22, 0
	v_mov_b32_e32 v23, 0
	v_mov_b32_e32 v24, 0
	v_mov_b32_e32 v25, 0
	v_mov_b32_e32 v26, 0
	v_mov_b32_e32 v27, 0
	v_mov_b32_e32 v28, 0
	v_mov_b32_e32 v29, 0
	v_mov_b32_e32 v30, 0
	v_mov_b32_e32 v31, 0
	s_cbranch_vccnz .LBB0_473
	s_lshl_b64 s[20:21], s[52:53], 1
	v_readlane_b32 s12, v254, 40
	s_add_u32 s12, s12, s20
	v_readlane_b32 s20, v254, 41
	s_addc_u32 s21, s20, s21
	s_lshl_b32 s20, s48, 1
	s_add_u32 s20, s12, s20
	s_addc_u32 s21, s21, 0
	v_lshl_add_u64 v[16:17], s[6:7], 0, v[58:59]
	v_mov_b32_e32 v71, v33
	v_lshl_add_u64 v[90:91], v[16:17], 0, v[32:33]
	v_lshl_add_u64 v[16:17], s[20:21], 0, v[70:71]
	v_lshl_add_u64 v[92:93], v[16:17], 0, v[32:33]
	global_load_dwordx4 v[16:19], v[90:91], off
	global_load_dwordx4 v[20:23], v[92:93], off
	global_load_dwordx4 v[82:85], v[90:91], off offset:32
	global_load_dwordx4 v[86:89], v[92:93], off offset:32
	global_load_dwordx4 v[112:115], v[90:91], off offset:64
	global_load_dwordx4 v[116:119], v[92:93], off offset:64
	global_load_dwordx4 v[120:123], v[90:91], off offset:96
	global_load_dwordx4 v[124:127], v[92:93], off offset:96
	global_load_dwordx4 v[128:131], v[90:91], off offset:128
	global_load_dwordx4 v[132:135], v[92:93], off offset:128
	global_load_dwordx4 v[136:139], v[90:91], off offset:160
	global_load_dwordx4 v[140:143], v[92:93], off offset:160
	global_load_dwordx4 v[148:151], v[90:91], off offset:192
	global_load_dwordx4 v[152:155], v[92:93], off offset:192
	global_load_dwordx4 v[156:159], v[90:91], off offset:224
	global_load_dwordx4 v[160:163], v[92:93], off offset:224
	s_waitcnt vmcnt(14)
	v_mfma_f32_32x32x16_bf16 v[16:31], v[16:19], v[20:23], 0
	s_waitcnt vmcnt(12)
	v_mfma_f32_32x32x16_bf16 v[16:31], v[82:85], v[86:89], v[16:31]
	s_waitcnt vmcnt(10)
	v_mfma_f32_32x32x16_bf16 v[16:31], v[112:115], v[116:119], v[16:31]
	s_waitcnt vmcnt(8)
	v_mfma_f32_32x32x16_bf16 v[16:31], v[120:123], v[124:127], v[16:31]
	s_waitcnt vmcnt(6)
	v_mfma_f32_32x32x16_bf16 v[16:31], v[128:131], v[132:135], v[16:31]
	s_waitcnt vmcnt(4)
	v_mfma_f32_32x32x16_bf16 v[16:31], v[136:139], v[140:143], v[16:31]
	s_waitcnt vmcnt(2)
	v_mfma_f32_32x32x16_bf16 v[16:31], v[148:151], v[152:155], v[16:31]
	s_waitcnt vmcnt(0)
	v_mfma_f32_32x32x16_bf16 v[16:31], v[156:159], v[160:163], v[16:31]

; #define LAS __attribute__((address_space(3)))
; DI void prep_phase(PARAMS P, int l, int g, LAS unsigned char* lds, int wave, int lane) {
;     ...
;         __syncthreads();
;         {
;             const int r = lane & 31, hh = lane >> 5;
; #pragma unroll 1
;             for (int cbk = wave * 6; cbk < wave * 6 + 6; ++cbk) {
;                 const int mt = cbk >> 4, hd = (cbk >> 2) & 3, nb = cbk & 3;
;                 const bf16_t* wt = wm + (size_t)(mt * 4 + hd) * 16384 + (size_t)(32 * nb + r) * 128 + 8 * hh;
;                 const LAS bf16_t* al = (mt == 2 ? Xl : Cl) + r * 520 + hd * 128 + 8 * hh;
;                 f32x16 a0, a1;
; #pragma unroll
;                 for (int i = 0; i < 16; ++i) { a0[i] = 0.f; a1[i] = 0.f; }
; #pragma unroll
;                 for (int ks = 0; ks < 8; ++ks) {
;                     const bf16x8 b = *(const bf16x8*)(wt + 16 * ks);
.LBB0_743:
	s_or_b32 s2, s6, 32
	s_lshl_b32 s3, s64, 2
	s_mov_b32 s7, 0
	s_mov_b32 s16, s61
	s_waitcnt lgkmcnt(0)
	s_barrier
	s_waitcnt vmcnt(0)
	s_mov_b32 s98, s60
	s_ashr_i32 s99, s98, 4
	s_bfe_u32 s100, s98, 0x20002
	s_lshl_b32 s99, s99, 2
	s_or_b32 s99, s99, s100
	s_lshl_b32 s100, s99, 15
	s_mov_b32 s101, 0
	s_add_u32 s100, s19, s100
	s_addc_u32 s101, s35, s101
	s_and_b32 s98, s16, 0x60
	v_or_b32_e32 v172, s98, v35
	v_lshlrev_b32_e32 v172, 8, v172
	v_mov_b32_e32 v173, 0
	v_lshl_add_u64 v[174:175], s[100:101], 0, v[172:173]
	v_mov_b32_e32 v176, v86
	v_mov_b32_e32 v177, 0
	v_lshl_add_u64 v[174:175], v[174:175], 0, v[176:177]
	global_load_dwordx4 v[164:167], v[174:175], off
	global_load_dwordx4 v[168:171], v[174:175], off offset:32
	global_load_dwordx4 v[140:143], v[174:175], off offset:64
	global_load_dwordx4 v[144:147], v[174:175], off offset:96
	global_load_dwordx4 v[148:151], v[174:175], off offset:128
	global_load_dwordx4 v[152:155], v[174:175], off offset:160
	global_load_dwordx4 v[156:159], v[174:175], off offset:192
	global_load_dwordx4 v[160:163], v[174:175], off offset:224
	s_waitcnt vmcnt(0)
	s_branch .LBB0_746

; #define LAS __attribute__((address_space(3)))
; #define MFMA32(a, b, c) __builtin_amdgcn_mfma_f32_32x32x16_bf16((a), (b), (c), 0, 0, 0)
; DI void prep_phase(PARAMS P, int l, int g, LAS unsigned char* lds, int wave, int lane) {
;     ...
;             for (int cbk = wave * 6; cbk < wave * 6 + 6; ++cbk) {
;                 const int mt = cbk >> 4, hd = (cbk >> 2) & 3, nb = cbk & 3;
;                 const bf16_t* wt = wm + (size_t)(mt * 4 + hd) * 16384 + (size_t)(32 * nb + r) * 128 + 8 * hh;
;                 const LAS bf16_t* al = (mt == 2 ? Xl : Cl) + r * 520 + hd * 128 + 8 * hh;
;                 f32x16 a0, a1;
; #pragma unroll
;                 for (int i = 0; i < 16; ++i) { a0[i] = 0.f; a1[i] = 0.f; }
; #pragma unroll
;                 for (int ks = 0; ks < 8; ++ks) {
;                     const bf16x8 b = *(const bf16x8*)(wt + 16 * ks);
;                     const bf16x8 x0 = *(const LAS bf16x8*)(al + 16 * ks), x1 = *(const LAS bf16x8*)(al + 32 * 520 + 16 * ks);
;                     a0 = MFMA32(x0, b, a0); a1 = MFMA32(x1, b, a1);
;                 }
;                 const int e = hd * 128 + 32 * nb + r;
.LBB0_746:
	s_add_i32 s33, s60, s7
	s_ashr_i32 s64, s33, 4
	s_bfe_u32 s17, s33, 0x20002
	s_lshl_b32 s4, s64, 2
	s_or_b32 s4, s4, s17
	s_ashr_i32 s5, s4, 31
	s_lshl_b64 s[4:5], s[4:5], 15
	s_add_u32 s4, s19, s4
	s_addc_u32 s5, s35, s5
	s_and_b32 s20, s16, 0x60
	v_or_b32_e32 v125, s20, v35
	v_lshlrev_b32_e32 v32, 8, v125
	s_waitcnt lgkmcnt(0)
	v_lshl_add_u64 v[0:1], s[4:5], 0, v[32:33]
	v_mov_b32_e32 v87, v33
	v_lshl_add_u64 v[88:89], v[0:1], 0, v[86:87]
	s_cmp_eq_u32 s64, 2
	s_cselect_b32 s4, s27, 0
	s_lshl_b32 s21, s17, 8
	s_add_i32 s4, s21, s4
	v_add3_u32 v32, s4, v93, v86
	ds_read_b128 v[20:23], v32 offset:33280
	ds_read_b128 v[0:3], v32
	ds_read_b128 v[126:129], v32 offset:32
	ds_read_b128 v[134:137], v32 offset:33312
	s_mov_b64 s[4:5], -1
	s_cmp_lg_u32 s64, 1
	s_waitcnt vmcnt(39) lgkmcnt(2)
	v_mfma_f32_32x32x16_bf16 v[0:15], v[0:3], v[164:167], 0
	s_waitcnt vmcnt(38) lgkmcnt(1)
	v_mfma_f32_32x32x16_bf16 v[0:15], v[126:129], v[168:171], v[0:15]
	v_mfma_f32_32x32x16_bf16 v[16:31], v[20:23], v[164:167], 0
	s_waitcnt lgkmcnt(0)
	v_mfma_f32_32x32x16_bf16 v[16:31], v[134:137], v[168:171], v[16:31]
	ds_read_b128 v[130:133], v32 offset:64
	ds_read_b128 v[134:137], v32 offset:33344
	s_waitcnt vmcnt(37) lgkmcnt(1)
	v_mfma_f32_32x32x16_bf16 v[0:15], v[130:133], v[140:143], v[0:15]
	s_waitcnt lgkmcnt(0)
	v_mfma_f32_32x32x16_bf16 v[16:31], v[134:137], v[140:143], v[16:31]
	ds_read_b128 v[130:133], v32 offset:96
	ds_read_b128 v[134:137], v32 offset:33376
	s_waitcnt vmcnt(36) lgkmcnt(1)
	v_mfma_f32_32x32x16_bf16 v[0:15], v[130:133], v[144:147], v[0:15]
	s_waitcnt lgkmcnt(0)
	v_mfma_f32_32x32x16_bf16 v[16:31], v[134:137], v[144:147], v[16:31]
	ds_read_b128 v[130:133], v32 offset:128
	ds_read_b128 v[134:137], v32 offset:33408
	s_waitcnt vmcnt(35) lgkmcnt(1)
	v_mfma_f32_32x32x16_bf16 v[0:15], v[130:133], v[148:151], v[0:15]
	s_waitcnt lgkmcnt(0)
	v_mfma_f32_32x32x16_bf16 v[16:31], v[134:137], v[148:151], v[16:31]
	ds_read_b128 v[130:133], v32 offset:160
	ds_read_b128 v[134:137], v32 offset:33440
	s_waitcnt vmcnt(34) lgkmcnt(1)
	v_mfma_f32_32x32x16_bf16 v[0:15], v[130:133], v[152:155], v[0:15]
	s_waitcnt lgkmcnt(0)
	v_mfma_f32_32x32x16_bf16 v[16:31], v[134:137], v[152:155], v[16:31]
	ds_read_b128 v[130:133], v32 offset:192
	ds_read_b128 v[134:137], v32 offset:33472
	s_waitcnt vmcnt(33) lgkmcnt(1)
	v_mfma_f32_32x32x16_bf16 v[0:15], v[130:133], v[156:159], v[0:15]
	s_waitcnt lgkmcnt(0)
	v_mfma_f32_32x32x16_bf16 v[16:31], v[134:137], v[156:159], v[16:31]
	ds_read_b128 v[130:133], v32 offset:224
	ds_read_b128 v[134:137], v32 offset:33504
	v_lshl_or_b32 v32, s17, 7, v125
	v_lshlrev_b32_e32 v32, 1, v32
	s_waitcnt vmcnt(32) lgkmcnt(1)
	v_mfma_f32_32x32x16_bf16 v[0:15], v[130:133], v[160:163], v[0:15]
	s_waitcnt lgkmcnt(0)
	v_mfma_f32_32x32x16_bf16 v[16:31], v[134:137], v[160:163], v[16:31]
	s_add_i32 s98, s33, 1
	s_ashr_i32 s99, s98, 4
	s_bfe_u32 s100, s98, 0x20002
	s_lshl_b32 s99, s99, 2
	s_or_b32 s99, s99, s100
	s_lshl_b32 s100, s99, 15
	s_mov_b32 s101, 0
	s_add_u32 s100, s19, s100
	s_addc_u32 s101, s35, s101
	s_add_i32 s98, s16, 32
	s_and_b32 s98, s98, 0x60
	v_or_b32_e32 v172, s98, v35
	v_lshlrev_b32_e32 v172, 8, v172
	v_mov_b32_e32 v173, 0
	v_lshl_add_u64 v[174:175], s[100:101], 0, v[172:173]
	v_mov_b32_e32 v176, v86
	v_mov_b32_e32 v177, 0
	v_lshl_add_u64 v[174:175], v[174:175], 0, v[176:177]
	global_load_dwordx4 v[164:167], v[174:175], off
	global_load_dwordx4 v[168:171], v[174:175], off offset:32
	global_load_dwordx4 v[140:143], v[174:175], off offset:64
	global_load_dwordx4 v[144:147], v[174:175], off offset:96
	global_load_dwordx4 v[148:151], v[174:175], off offset:128
	global_load_dwordx4 v[152:155], v[174:175], off offset:160
	global_load_dwordx4 v[156:159], v[174:175], off offset:192
	global_load_dwordx4 v[160:163], v[174:175], off offset:224
	s_cmp_lg_u32 s64, 1
	s_cbranch_scc1 .LBB0_748
	s_andn2_b64 vcc, exec, s[4:5]
	s_cbranch_vccnz .LBB0_745
	s_branch .LBB0_749
